# residual GEMMs: store/prefetch drain placed at the end of the per-unit accumulator zeroing (moved in P5, added in P8)
# speedup vs baseline: 1.0004x; 1.0004x over previous
; template <class Epi, class Sched>
; __device__ __forceinline__ void gemm_phase(PG8_LAS unsigned char* lds, const Gemm g, const Sched& S, const Epi& E) {
;     ...
; #pragma unroll
;         for (int a = 0; a < 2; ++a)
; #pragma unroll
;             for (int b = 0; b < 2; ++b)
; #pragma unroll
;                 for (int m = 0; m < 4; ++m)
; #pragma unroll
;                     for (int n = 0; n < 2; ++n) acc[a][b][m][n] = (f32x4){0.f, 0.f, 0.f, 0.f};
;         cur = nxt; cA = nA; cB = nB; cnt = ncnt; ++ui;
.LBB0_974:
	s_add_i32 s5, s21, -2
	s_add_u32 s25, s16, 0x100
	v_mov_b32_e32 v2, 0
	s_addc_u32 s45, s17, 0
	s_mov_b32 s26, 0
	v_mov_b32_e32 v3, v2
	v_mov_b32_e32 v4, v2
	v_mov_b32_e32 v5, v2
	v_mov_b32_e32 v6, v2
	v_mov_b32_e32 v7, v2
	v_mov_b32_e32 v8, v2
	v_mov_b32_e32 v9, v2
	v_mov_b32_e32 v10, v2
	v_mov_b32_e32 v11, v2
	v_mov_b32_e32 v12, v2
	v_mov_b32_e32 v13, v2
	v_mov_b32_e32 v14, v2
	v_mov_b32_e32 v15, v2
	v_mov_b32_e32 v16, v2
	v_mov_b32_e32 v17, v2
	v_mov_b32_e32 v26, v2
	v_mov_b32_e32 v27, v2
	v_mov_b32_e32 v28, v2
	v_mov_b32_e32 v29, v2
	v_mov_b32_e32 v30, v2
	v_mov_b32_e32 v31, v2
	v_mov_b32_e32 v32, v2
	v_mov_b32_e32 v33, v2
	v_mov_b32_e32 v42, v2
	v_mov_b32_e32 v43, v2
	v_mov_b32_e32 v44, v2
	v_mov_b32_e32 v45, v2
	v_mov_b32_e32 v46, v2
	v_mov_b32_e32 v47, v2
	v_mov_b32_e32 v48, v2
	v_mov_b32_e32 v49, v2
	v_mov_b32_e32 v18, v2
	v_mov_b32_e32 v19, v2
	v_mov_b32_e32 v20, v2
	v_mov_b32_e32 v21, v2
	v_mov_b32_e32 v22, v2
	v_mov_b32_e32 v23, v2
	v_mov_b32_e32 v24, v2
	v_mov_b32_e32 v25, v2
	v_mov_b32_e32 v34, v2
	v_mov_b32_e32 v35, v2
	v_mov_b32_e32 v36, v2
	v_mov_b32_e32 v37, v2
	v_mov_b32_e32 v38, v2
	v_mov_b32_e32 v39, v2
	v_mov_b32_e32 v40, v2
	v_mov_b32_e32 v41, v2
	v_mov_b32_e32 v50, v2
	v_mov_b32_e32 v51, v2
	v_mov_b32_e32 v52, v2
	v_mov_b32_e32 v53, v2
	v_mov_b32_e32 v54, v2
	v_mov_b32_e32 v55, v2
	v_mov_b32_e32 v56, v2
	v_mov_b32_e32 v57, v2
	v_mov_b32_e32 v58, v2
	v_mov_b32_e32 v59, v2
	v_mov_b32_e32 v60, v2
	v_mov_b32_e32 v61, v2
	v_mov_b32_e32 v62, v2
	v_mov_b32_e32 v63, v2
	v_mov_b32_e32 v64, v2
	v_mov_b32_e32 v65, v2
	v_mov_b32_e32 v66, v2
	v_mov_b32_e32 v67, v2
	v_mov_b32_e32 v68, v2
	v_mov_b32_e32 v69, v2
	v_mov_b32_e32 v70, v2
	v_mov_b32_e32 v71, v2
	v_mov_b32_e32 v72, v2
	v_mov_b32_e32 v73, v2
	v_mov_b32_e32 v74, v2
	v_mov_b32_e32 v75, v2
	v_mov_b32_e32 v76, v2
	v_mov_b32_e32 v77, v2
	v_mov_b32_e32 v78, v2
	v_mov_b32_e32 v79, v2
	v_mov_b32_e32 v80, v2
	v_mov_b32_e32 v81, v2
	v_mov_b32_e32 v86, v2
	v_mov_b32_e32 v87, v2
	v_mov_b32_e32 v88, v2
	v_mov_b32_e32 v89, v2
	v_mov_b32_e32 v94, v2
	v_mov_b32_e32 v95, v2
	v_mov_b32_e32 v96, v2
	v_mov_b32_e32 v97, v2
	v_mov_b32_e32 v102, v2
	v_mov_b32_e32 v103, v2
	v_mov_b32_e32 v104, v2
	v_mov_b32_e32 v105, v2
	v_mov_b32_e32 v110, v2
	v_mov_b32_e32 v111, v2
	v_mov_b32_e32 v112, v2
	v_mov_b32_e32 v113, v2
	v_mov_b32_e32 v82, v2
	v_mov_b32_e32 v83, v2
	v_mov_b32_e32 v84, v2
	v_mov_b32_e32 v85, v2
	v_mov_b32_e32 v90, v2
	v_mov_b32_e32 v91, v2
	v_mov_b32_e32 v92, v2
	v_mov_b32_e32 v93, v2
	v_mov_b32_e32 v98, v2
	v_mov_b32_e32 v99, v2
	v_mov_b32_e32 v100, v2
	v_mov_b32_e32 v101, v2
	v_mov_b32_e32 v106, v2
	v_mov_b32_e32 v107, v2
	v_mov_b32_e32 v108, v2
	v_mov_b32_e32 v109, v2
	v_mov_b32_e32 v114, v2
	v_mov_b32_e32 v115, v2
	v_mov_b32_e32 v116, v2
	v_mov_b32_e32 v117, v2
	v_mov_b32_e32 v118, v2
	v_mov_b32_e32 v119, v2
	v_mov_b32_e32 v120, v2
	v_mov_b32_e32 v121, v2
	v_mov_b32_e32 v122, v2
	v_mov_b32_e32 v123, v2
	v_mov_b32_e32 v124, v2
	v_mov_b32_e32 v125, v2
	v_mov_b32_e32 v126, v2
	v_mov_b32_e32 v127, v2
	v_mov_b32_e32 v128, v2
	v_mov_b32_e32 v129, v2
	s_waitcnt vmcnt(0)

; template <class Epi, class Sched>
; __device__ __forceinline__ void gemm_phase(PG8_LAS unsigned char* lds, const Gemm g, const Sched& S, const Epi& E) {
;     ...
; #pragma unroll
;         for (int a = 0; a < 2; ++a)
; #pragma unroll
;             for (int b = 0; b < 2; ++b)
; #pragma unroll
;                 for (int m = 0; m < 4; ++m)
; #pragma unroll
;                     for (int n = 0; n < 2; ++n) acc[a][b][m][n] = (f32x4){0.f, 0.f, 0.f, 0.f};
;         cur = nxt; cA = nA; cB = nB; cnt = ncnt; ++ui;
.LBB0_1194:
	s_add_i32 s5, s19, -2
	s_add_u32 s21, s16, 0x100
	v_mov_b32_e32 v2, 0
	s_addc_u32 s25, s17, 0
	s_mov_b32 s26, 0
	v_mov_b32_e32 v3, v2
	v_mov_b32_e32 v4, v2
	v_mov_b32_e32 v5, v2
	v_mov_b32_e32 v6, v2
	v_mov_b32_e32 v7, v2
	v_mov_b32_e32 v8, v2
	v_mov_b32_e32 v9, v2
	v_mov_b32_e32 v10, v2
	v_mov_b32_e32 v11, v2
	v_mov_b32_e32 v12, v2
	v_mov_b32_e32 v13, v2
	v_mov_b32_e32 v14, v2
	v_mov_b32_e32 v15, v2
	v_mov_b32_e32 v16, v2
	v_mov_b32_e32 v17, v2
	v_mov_b32_e32 v26, v2
	v_mov_b32_e32 v27, v2
	v_mov_b32_e32 v28, v2
	v_mov_b32_e32 v29, v2
	v_mov_b32_e32 v30, v2
	v_mov_b32_e32 v31, v2
	v_mov_b32_e32 v32, v2
	v_mov_b32_e32 v33, v2
	v_mov_b32_e32 v42, v2
	v_mov_b32_e32 v43, v2
	v_mov_b32_e32 v44, v2
	v_mov_b32_e32 v45, v2
	v_mov_b32_e32 v46, v2
	v_mov_b32_e32 v47, v2
	v_mov_b32_e32 v48, v2
	v_mov_b32_e32 v49, v2
	v_mov_b32_e32 v18, v2
	v_mov_b32_e32 v19, v2
	v_mov_b32_e32 v20, v2
	v_mov_b32_e32 v21, v2
	v_mov_b32_e32 v22, v2
	v_mov_b32_e32 v23, v2
	v_mov_b32_e32 v24, v2
	v_mov_b32_e32 v25, v2
	v_mov_b32_e32 v34, v2
	v_mov_b32_e32 v35, v2
	v_mov_b32_e32 v36, v2
	v_mov_b32_e32 v37, v2
	v_mov_b32_e32 v38, v2
	v_mov_b32_e32 v39, v2
	v_mov_b32_e32 v40, v2
	v_mov_b32_e32 v41, v2
	v_mov_b32_e32 v50, v2
	v_mov_b32_e32 v51, v2
	v_mov_b32_e32 v52, v2
	v_mov_b32_e32 v53, v2
	v_mov_b32_e32 v54, v2
	v_mov_b32_e32 v55, v2
	v_mov_b32_e32 v56, v2
	v_mov_b32_e32 v57, v2
	v_mov_b32_e32 v58, v2
	v_mov_b32_e32 v59, v2
	v_mov_b32_e32 v60, v2
	v_mov_b32_e32 v61, v2
	v_mov_b32_e32 v62, v2
	v_mov_b32_e32 v63, v2
	v_mov_b32_e32 v64, v2
	v_mov_b32_e32 v65, v2
	v_mov_b32_e32 v66, v2
	v_mov_b32_e32 v67, v2
	v_mov_b32_e32 v68, v2
	v_mov_b32_e32 v69, v2
	v_mov_b32_e32 v70, v2
	v_mov_b32_e32 v71, v2
	v_mov_b32_e32 v72, v2
	v_mov_b32_e32 v73, v2
	v_mov_b32_e32 v74, v2
	v_mov_b32_e32 v75, v2
	v_mov_b32_e32 v76, v2
	v_mov_b32_e32 v77, v2
	v_mov_b32_e32 v78, v2
	v_mov_b32_e32 v79, v2
	v_mov_b32_e32 v80, v2
	v_mov_b32_e32 v81, v2
	v_mov_b32_e32 v86, v2
	v_mov_b32_e32 v87, v2
	v_mov_b32_e32 v88, v2
	v_mov_b32_e32 v89, v2
	v_mov_b32_e32 v94, v2
	v_mov_b32_e32 v95, v2
	v_mov_b32_e32 v96, v2
	v_mov_b32_e32 v97, v2
	v_mov_b32_e32 v102, v2
	v_mov_b32_e32 v103, v2
	v_mov_b32_e32 v104, v2
	v_mov_b32_e32 v105, v2
	v_mov_b32_e32 v110, v2
	v_mov_b32_e32 v111, v2
	v_mov_b32_e32 v112, v2
	v_mov_b32_e32 v113, v2
	v_mov_b32_e32 v82, v2
	v_mov_b32_e32 v83, v2
	v_mov_b32_e32 v84, v2
	v_mov_b32_e32 v85, v2
	v_mov_b32_e32 v90, v2
	v_mov_b32_e32 v91, v2
	v_mov_b32_e32 v92, v2
	v_mov_b32_e32 v93, v2
	v_mov_b32_e32 v98, v2
	v_mov_b32_e32 v99, v2
	v_mov_b32_e32 v100, v2
	v_mov_b32_e32 v101, v2
	v_mov_b32_e32 v106, v2
	v_mov_b32_e32 v107, v2
	v_mov_b32_e32 v108, v2
	v_mov_b32_e32 v109, v2
	v_mov_b32_e32 v114, v2
	v_mov_b32_e32 v115, v2
	v_mov_b32_e32 v116, v2
	v_mov_b32_e32 v117, v2
	v_mov_b32_e32 v118, v2
	v_mov_b32_e32 v119, v2
	v_mov_b32_e32 v120, v2
	v_mov_b32_e32 v121, v2
	v_mov_b32_e32 v122, v2
	v_mov_b32_e32 v123, v2
	v_mov_b32_e32 v124, v2
	v_mov_b32_e32 v125, v2
	v_mov_b32_e32 v126, v2
	v_mov_b32_e32 v127, v2
	v_mov_b32_e32 v128, v2
	v_mov_b32_e32 v129, v2
	s_waitcnt vmcnt(0)
